# ma_ret j-loop: LDS operand reads software-pipelined 8 deep with counted lgkmcnt instead of read-wait-mfma chain
# speedup vs baseline: 1.0018x; 1.0018x over previous
; #define LAS __attribute__((address_space(3)))
; __device__ __forceinline__ f32x4 mma16(bf16x8 a, bf16x8 b, f32x4 c) { return __builtin_amdgcn_mfma_f32_16x16x32_bf16(a, b, c, 0, 0, 0); }
; template <int F> __device__ __forceinline__ void st_T(ldsp dst, int dp_unused, const u32x4 (&r)[F / 64], int wave, int lane) {
;     ...
;     for (int it = 0; it < F / 64; ++it) { const u32x4 w = r[it];
; #pragma unroll
;         for (int i = 0; i < 4; ++i) {
;             *(LAS bf16_t*)(base + (64 * it + 2 * i) * 144) = (bf16_t)(w[i] & 0xffffu);
;             *(LAS bf16_t*)(base + (64 * it + 2 * i + 1) * 144) = (bf16_t)(w[i] >> 16); } }
; __device__ __forceinline__ void ma_ret_item(const Params& p, ldsp lds, int item) {
;     ...
;     for (int j = 0; j < 4; ++j) { const size_t rowj = (size_t)b * 2048 + (sc * 4 + j) * 64;
;         st_T<256>(KTt, 72, kr, wave, lane); st_T<128>(VTt, 72, vr, wave, lane);
;         __syncthreads();
;         if (j < 3) { const size_t rown = rowj + 64; ld_T<256>(kr, Pb + rown * NO + O_K + h * 256, NO, wave, lane); ld_T<128>(vr, Pb + rown * NO + O_V + h * 512 + es * 128, NO, wave, lane); }
; #pragma unroll
;         for (int ks = 0; ks < 2; ++ks) { const bf16x8 bf = ldfrag(VTt, (16 * wave + l15) * 72 + 32 * ks + 8 * q4);
; #pragma unroll
;             for (int i = 0; i < 16; ++i) acc[i] = mma16(ldfrag(KTt, (16 * i + l15) * 72 + 32 * ks + 8 * q4), bf, acc[i]); }
;         __syncthreads(); }
.LBB0_678:
	s_waitcnt vmcnt(5)
	ds_write_b16 v100, v22
	ds_write_b16_d16_hi v100, v22 offset:144
	ds_write_b16 v100, v23 offset:288
	ds_write_b16_d16_hi v100, v23 offset:432
	ds_write_b16 v100, v24 offset:576
	ds_write_b16_d16_hi v100, v24 offset:720
	ds_write_b16 v100, v25 offset:864
	ds_write_b16_d16_hi v100, v25 offset:1008
	s_waitcnt vmcnt(4)
	ds_write_b16 v100, v18 offset:9216
	ds_write_b16_d16_hi v100, v18 offset:9360
	ds_write_b16 v100, v19 offset:9504
	ds_write_b16_d16_hi v100, v19 offset:9648
	ds_write_b16 v100, v20 offset:9792
	ds_write_b16_d16_hi v100, v20 offset:9936
	ds_write_b16 v100, v21 offset:10080
	ds_write_b16_d16_hi v100, v21 offset:10224
	s_waitcnt vmcnt(3)
	ds_write_b16 v100, v12 offset:18432
	ds_write_b16_d16_hi v100, v12 offset:18576
	ds_write_b16 v100, v13 offset:18720
	ds_write_b16_d16_hi v100, v13 offset:18864
	ds_write_b16 v100, v14 offset:19008
	ds_write_b16_d16_hi v100, v14 offset:19152
	ds_write_b16 v100, v15 offset:19296
	ds_write_b16_d16_hi v100, v15 offset:19440
	s_waitcnt vmcnt(2)
	ds_write_b16 v100, v4 offset:27648
	ds_write_b16_d16_hi v100, v4 offset:27792
	ds_write_b16 v100, v5 offset:27936
	ds_write_b16_d16_hi v100, v5 offset:28080
	ds_write_b16 v100, v6 offset:28224
	ds_write_b16_d16_hi v100, v6 offset:28368
	ds_write_b16 v100, v7 offset:28512
	ds_write_b16_d16_hi v100, v7 offset:28656
	s_waitcnt vmcnt(1)
	ds_write_b16 v100, v8 offset:36864
	ds_write_b16_d16_hi v100, v8 offset:37008
	ds_write_b16 v100, v9 offset:37152
	ds_write_b16_d16_hi v100, v9 offset:37296
	ds_write_b16 v100, v10 offset:37440
	ds_write_b16_d16_hi v100, v10 offset:37584
	ds_write_b16 v100, v11 offset:37728
	ds_write_b16_d16_hi v100, v11 offset:37872
	s_waitcnt vmcnt(0)
	ds_write_b16 v100, v0 offset:46080
	ds_write_b16_d16_hi v100, v0 offset:46224
	ds_write_b16 v100, v1 offset:46368
	ds_write_b16_d16_hi v100, v1 offset:46512
	ds_write_b16 v100, v2 offset:46656
	ds_write_b16_d16_hi v100, v2 offset:46800
	ds_write_b16 v100, v3 offset:46944
	ds_write_b16_d16_hi v100, v3 offset:47088
	v_lshl_add_u64 v[0:1], v[98:99], 0, s[10:11]
	s_waitcnt lgkmcnt(0)
	s_barrier
	global_load_dwordx4 v[22:25], v[0:1], off offset:-256
	global_load_dwordx4 v[18:21], v[0:1], off offset:-128
	global_load_dwordx4 v[12:15], v[0:1], off
	global_load_dwordx4 v[4:7], v[0:1], off offset:128
	v_lshl_add_u64 v[0:1], v[96:97], 0, s[10:11]
	v_add_co_u32_e32 v0, vcc, s54, v0
	s_add_u32 s10, s10, 0xc0000
	s_nop 0
	v_addc_co_u32_e32 v1, vcc, 0, v1, vcc
	global_load_dwordx4 v[8:11], v[0:1], off
	s_nop 0
	global_load_dwordx4 v[0:3], v[0:1], off offset:128
	ds_read_b128 v[90:93], v130 offset:36864
	ds_read_b128 v[242:245], v130 offset:36928
	ds_read_b128 v[210:213], v132
	ds_read_b128 v[214:217], v131
	ds_read_b128 v[218:221], v129
	ds_read_b128 v[222:225], v128
	ds_read_b128 v[226:229], v127
	ds_read_b128 v[230:233], v126
	ds_read_b128 v[234:237], v125
	ds_read_b128 v[238:241], v124
	s_addc_u32 s11, s11, 0
	s_cmp_lg_u32 s10, 0x240000
	s_waitcnt lgkmcnt(7)
	v_mfma_f32_16x16x32_bf16 v[26:29], v[210:213], v[90:93], v[26:29]
	ds_read_b128 v[210:213], v123
	s_waitcnt lgkmcnt(7)
	v_mfma_f32_16x16x32_bf16 v[34:37], v[214:217], v[90:93], v[34:37]
	ds_read_b128 v[214:217], v122
	s_waitcnt lgkmcnt(7)
	v_mfma_f32_16x16x32_bf16 v[38:41], v[218:221], v[90:93], v[38:41]
	ds_read_b128 v[218:221], v121
	s_waitcnt lgkmcnt(7)
	v_mfma_f32_16x16x32_bf16 v[42:45], v[222:225], v[90:93], v[42:45]
	ds_read_b128 v[222:225], v120
	s_waitcnt lgkmcnt(7)
	v_mfma_f32_16x16x32_bf16 v[46:49], v[226:229], v[90:93], v[46:49]
	ds_read_b128 v[226:229], v119
	s_waitcnt lgkmcnt(7)
	v_mfma_f32_16x16x32_bf16 v[50:53], v[230:233], v[90:93], v[50:53]
	ds_read_b128 v[230:233], v118
	s_waitcnt lgkmcnt(7)
	v_mfma_f32_16x16x32_bf16 v[54:57], v[234:237], v[90:93], v[54:57]
	ds_read_b128 v[234:237], v117
	s_waitcnt lgkmcnt(7)
	v_mfma_f32_16x16x32_bf16 v[58:61], v[238:241], v[90:93], v[58:61]
	ds_read_b128 v[238:241], v116
	s_waitcnt lgkmcnt(7)
	v_mfma_f32_16x16x32_bf16 v[62:65], v[210:213], v[90:93], v[62:65]
	ds_read_b128 v[210:213], v115
	s_waitcnt lgkmcnt(7)
	v_mfma_f32_16x16x32_bf16 v[66:69], v[214:217], v[90:93], v[66:69]
	ds_read_b128 v[214:217], v114
	s_waitcnt lgkmcnt(7)
	v_mfma_f32_16x16x32_bf16 v[70:73], v[218:221], v[90:93], v[70:73]
	ds_read_b128 v[218:221], v113
	s_waitcnt lgkmcnt(7)
	v_mfma_f32_16x16x32_bf16 v[74:77], v[222:225], v[90:93], v[74:77]
	ds_read_b128 v[222:225], v112
	s_waitcnt lgkmcnt(7)
	v_mfma_f32_16x16x32_bf16 v[78:81], v[226:229], v[90:93], v[78:81]
	ds_read_b128 v[226:229], v111
	s_waitcnt lgkmcnt(7)
	v_mfma_f32_16x16x32_bf16 v[82:85], v[230:233], v[90:93], v[82:85]
	ds_read_b128 v[230:233], v110
	s_waitcnt lgkmcnt(7)
	v_mfma_f32_16x16x32_bf16 v[86:89], v[234:237], v[90:93], v[86:89]
	ds_read_b128 v[234:237], v109
	s_waitcnt lgkmcnt(7)
	v_mfma_f32_16x16x32_bf16 v[30:33], v[238:241], v[90:93], v[30:33]
	ds_read_b128 v[238:241], v108
	s_waitcnt lgkmcnt(7)
	v_mfma_f32_16x16x32_bf16 v[26:29], v[210:213], v[242:245], v[26:29]
	ds_read_b128 v[210:213], v107
	s_waitcnt lgkmcnt(7)
	v_mfma_f32_16x16x32_bf16 v[34:37], v[214:217], v[242:245], v[34:37]
	ds_read_b128 v[214:217], v106
	s_waitcnt lgkmcnt(7)
	v_mfma_f32_16x16x32_bf16 v[38:41], v[218:221], v[242:245], v[38:41]
	ds_read_b128 v[218:221], v105
	s_waitcnt lgkmcnt(7)
	v_mfma_f32_16x16x32_bf16 v[42:45], v[222:225], v[242:245], v[42:45]
	ds_read_b128 v[222:225], v104
	s_waitcnt lgkmcnt(7)
	v_mfma_f32_16x16x32_bf16 v[46:49], v[226:229], v[242:245], v[46:49]
	ds_read_b128 v[226:229], v103
	s_waitcnt lgkmcnt(7)
	v_mfma_f32_16x16x32_bf16 v[50:53], v[230:233], v[242:245], v[50:53]
	ds_read_b128 v[230:233], v102
	s_waitcnt lgkmcnt(7)
	v_mfma_f32_16x16x32_bf16 v[54:57], v[234:237], v[242:245], v[54:57]
	ds_read_b128 v[234:237], v101
	s_waitcnt lgkmcnt(7)
	v_mfma_f32_16x16x32_bf16 v[58:61], v[238:241], v[242:245], v[58:61]
	ds_read_b128 v[238:241], v16
	s_waitcnt lgkmcnt(7)
	v_mfma_f32_16x16x32_bf16 v[62:65], v[210:213], v[242:245], v[62:65]
	s_waitcnt lgkmcnt(6)
	v_mfma_f32_16x16x32_bf16 v[66:69], v[214:217], v[242:245], v[66:69]
	s_waitcnt lgkmcnt(5)
	v_mfma_f32_16x16x32_bf16 v[70:73], v[218:221], v[242:245], v[70:73]
	s_waitcnt lgkmcnt(4)
	v_mfma_f32_16x16x32_bf16 v[74:77], v[222:225], v[242:245], v[74:77]
	s_waitcnt lgkmcnt(3)
	v_mfma_f32_16x16x32_bf16 v[78:81], v[226:229], v[242:245], v[78:81]
	s_waitcnt lgkmcnt(2)
	v_mfma_f32_16x16x32_bf16 v[82:85], v[230:233], v[242:245], v[82:85]
	s_waitcnt lgkmcnt(1)
	v_mfma_f32_16x16x32_bf16 v[86:89], v[234:237], v[242:245], v[86:89]
	s_waitcnt lgkmcnt(0)
	s_barrier
; __device__ __forceinline__ f32x4 mma16(bf16x8 a, bf16x8 b, f32x4 c) { return __builtin_amdgcn_mfma_f32_16x16x32_bf16(a, b, c, 0, 0, 0); }
; __device__ __forceinline__ void ma_ret_item(const Params& p, ldsp lds, int item) {
;     ...
;     for (int j = 0; j < 4; ++j) { const size_t rowj = (size_t)b * 2048 + (sc * 4 + j) * 64;
;         st_T<256>(KTt, 72, kr, wave, lane); st_T<128>(VTt, 72, vr, wave, lane);
;         __syncthreads();
;         if (j < 3) { const size_t rown = rowj + 64; ld_T<256>(kr, Pb + rown * NO + O_K + h * 256, NO, wave, lane); ld_T<128>(vr, Pb + rown * NO + O_V + h * 512 + es * 128, NO, wave, lane); }
; #pragma unroll
;         for (int ks = 0; ks < 2; ++ks) { const bf16x8 bf = ldfrag(VTt, (16 * wave + l15) * 72 + 32 * ks + 8 * q4);
; #pragma unroll
;             for (int i = 0; i < 16; ++i) acc[i] = mma16(ldfrag(KTt, (16 * i + l15) * 72 + 32 * ks + 8 * q4), bf, acc[i]); }
;         __syncthreads(); }
	v_mfma_f32_16x16x32_bf16 v[30:33], v[238:241], v[242:245], v[30:33]
	s_cbranch_scc1 .LBB0_678
	s_waitcnt vmcnt(5)
	ds_write_b16 v100, v22
	ds_write_b16_d16_hi v100, v22 offset:144
	ds_write_b16 v100, v23 offset:288
	ds_write_b16_d16_hi v100, v23 offset:432
	ds_write_b16 v100, v24 offset:576
	ds_write_b16_d16_hi v100, v24 offset:720
	ds_write_b16 v100, v25 offset:864
	ds_write_b16_d16_hi v100, v25 offset:1008
	s_waitcnt vmcnt(4)
	ds_write_b16 v100, v18 offset:9216
	ds_write_b16_d16_hi v100, v18 offset:9360
	ds_write_b16 v100, v19 offset:9504
	ds_write_b16_d16_hi v100, v19 offset:9648
	ds_write_b16 v100, v20 offset:9792
	ds_write_b16_d16_hi v100, v20 offset:9936
	ds_write_b16 v100, v21 offset:10080
	ds_write_b16_d16_hi v100, v21 offset:10224
	s_waitcnt vmcnt(3)
	ds_write_b16 v100, v12 offset:18432
	ds_write_b16_d16_hi v100, v12 offset:18576
	ds_write_b16 v100, v13 offset:18720
	ds_write_b16_d16_hi v100, v13 offset:18864
	ds_write_b16 v100, v14 offset:19008
	ds_write_b16_d16_hi v100, v14 offset:19152
	ds_write_b16 v100, v15 offset:19296
	ds_write_b16_d16_hi v100, v15 offset:19440
	s_waitcnt vmcnt(2)
	ds_write_b16 v100, v4 offset:27648
	ds_write_b16_d16_hi v100, v4 offset:27792
	ds_write_b16 v100, v5 offset:27936
	ds_write_b16_d16_hi v100, v5 offset:28080
	ds_write_b16 v100, v6 offset:28224
	ds_write_b16_d16_hi v100, v6 offset:28368
	ds_write_b16 v100, v7 offset:28512
	ds_write_b16_d16_hi v100, v7 offset:28656
	s_waitcnt vmcnt(1)
	ds_write_b16 v100, v8 offset:36864
	ds_write_b16_d16_hi v100, v8 offset:37008
	ds_write_b16 v100, v9 offset:37152
	ds_write_b16_d16_hi v100, v9 offset:37296
	ds_write_b16 v100, v10 offset:37440
	ds_write_b16_d16_hi v100, v10 offset:37584
	ds_write_b16 v100, v11 offset:37728
	ds_write_b16_d16_hi v100, v11 offset:37872
	s_waitcnt vmcnt(0)
	ds_write_b16 v100, v0 offset:46080
	ds_write_b16_d16_hi v100, v0 offset:46224
	ds_write_b16 v100, v1 offset:46368
	ds_write_b16_d16_hi v100, v1 offset:46512
	ds_write_b16 v100, v2 offset:46656
	ds_write_b16_d16_hi v100, v2 offset:46800
	ds_write_b16 v100, v3 offset:46944
	ds_write_b16_d16_hi v100, v3 offset:47088
	s_waitcnt lgkmcnt(0)
	s_barrier
	ds_read_b128 v[0:3], v132
	ds_read_b128 v[4:7], v130 offset:36864
	ds_read_b128 v[8:11], v131
	ds_read_b128 v[12:15], v130 offset:36928
	ds_read_b128 v[18:21], v129
	ds_read_b128 v[22:25], v128
	s_waitcnt lgkmcnt(4)
	v_mfma_f32_16x16x32_bf16 v[0:3], v[0:3], v[4:7], v[26:29]
	s_ashr_i32 s1, s0, 31
	v_readlane_b32 s10, v255, 9
	s_lshl_b64 s[0:1], s[0:1], 12
	s_waitcnt lgkmcnt(3)
	v_mfma_f32_16x16x32_bf16 v[8:11], v[8:11], v[4:7], v[34:37]
	ds_read_b128 v[26:29], v127
	v_readlane_b32 s11, v255, 10
	s_or_b64 s[0:1], s[0:1], s[10:11]
	s_waitcnt lgkmcnt(2)
	v_mfma_f32_16x16x32_bf16 v[18:21], v[18:21], v[4:7], v[38:41]
	ds_read_b128 v[34:37], v126
	s_ashr_i32 s9, s8, 31
	s_add_i32 s12, s12, 1
	s_waitcnt lgkmcnt(2)
	v_mfma_f32_16x16x32_bf16 v[22:25], v[22:25], v[4:7], v[42:45]
	ds_read_b128 v[38:41], v125
	s_cmp_eq_u32 s12, 4
	s_nop 0
	ds_read_b128 v[42:45], v124
	s_waitcnt lgkmcnt(3)
	v_mfma_f32_16x16x32_bf16 v[26:29], v[26:29], v[4:7], v[46:49]
	s_waitcnt lgkmcnt(2)
	v_mfma_f32_16x16x32_bf16 v[34:37], v[34:37], v[4:7], v[50:53]
	s_nop 0
	ds_read_b128 v[46:49], v123
	s_nop 0
	ds_read_b128 v[50:53], v122
	s_waitcnt lgkmcnt(3)
	v_mfma_f32_16x16x32_bf16 v[38:41], v[38:41], v[4:7], v[54:57]
	s_waitcnt lgkmcnt(2)
	v_mfma_f32_16x16x32_bf16 v[42:45], v[42:45], v[4:7], v[58:61]
	s_nop 0
	ds_read_b128 v[54:57], v121
	s_nop 0
	ds_read_b128 v[58:61], v120
	s_waitcnt lgkmcnt(3)
	v_mfma_f32_16x16x32_bf16 v[46:49], v[46:49], v[4:7], v[62:65]
	s_waitcnt lgkmcnt(2)
	v_mfma_f32_16x16x32_bf16 v[50:53], v[50:53], v[4:7], v[66:69]
	s_nop 0
	ds_read_b128 v[62:65], v119
	s_nop 0
	ds_read_b128 v[66:69], v118
	s_waitcnt lgkmcnt(3)
	v_mfma_f32_16x16x32_bf16 v[54:57], v[54:57], v[4:7], v[70:73]
	s_waitcnt lgkmcnt(2)
	v_mfma_f32_16x16x32_bf16 v[58:61], v[58:61], v[4:7], v[74:77]
	s_nop 0
	ds_read_b128 v[70:73], v117
	s_nop 0
	ds_read_b128 v[74:77], v116
	s_waitcnt lgkmcnt(3)
	v_mfma_f32_16x16x32_bf16 v[62:65], v[62:65], v[4:7], v[78:81]
	s_waitcnt lgkmcnt(2)
	v_mfma_f32_16x16x32_bf16 v[66:69], v[66:69], v[4:7], v[82:85]
	s_nop 0
	ds_read_b128 v[78:81], v115
	s_waitcnt lgkmcnt(2)
	v_mfma_f32_16x16x32_bf16 v[70:73], v[70:73], v[4:7], v[86:89]
	s_waitcnt lgkmcnt(1)
	v_mfma_f32_16x16x32_bf16 v[4:7], v[74:77], v[4:7], v[30:33]
	ds_read_b128 v[74:77], v113
	s_nop 1
	ds_read_b128 v[30:33], v114
	s_waitcnt lgkmcnt(0)
	v_mfma_f32_16x16x32_bf16 v[8:11], v[30:33], v[12:15], v[8:11]
	ds_read_b128 v[30:33], v112
	v_mfma_f32_16x16x32_bf16 v[18:21], v[74:77], v[12:15], v[18:21]
	ds_read_b128 v[74:77], v111
	s_waitcnt lgkmcnt(1)
	v_mfma_f32_16x16x32_bf16 v[22:25], v[30:33], v[12:15], v[22:25]
	ds_read_b128 v[30:33], v110
	s_waitcnt lgkmcnt(1)
	v_mfma_f32_16x16x32_bf16 v[26:29], v[74:77], v[12:15], v[26:29]
	ds_read_b128 v[74:77], v109
	s_waitcnt lgkmcnt(1)
	v_mfma_f32_16x16x32_bf16 v[30:33], v[30:33], v[12:15], v[34:37]
	s_nop 2
	ds_read_b128 v[34:37], v108
	s_waitcnt lgkmcnt(1)
	v_mfma_f32_16x16x32_bf16 v[38:41], v[74:77], v[12:15], v[38:41]
	ds_read_b128 v[74:77], v107
	s_waitcnt lgkmcnt(1)
	v_mfma_f32_16x16x32_bf16 v[34:37], v[34:37], v[12:15], v[42:45]
	s_nop 2
	ds_read_b128 v[42:45], v106
	s_waitcnt lgkmcnt(1)
	v_mfma_f32_16x16x32_bf16 v[46:49], v[74:77], v[12:15], v[46:49]
	ds_read_b128 v[74:77], v105
	s_waitcnt lgkmcnt(1)
	v_mfma_f32_16x16x32_bf16 v[42:45], v[42:45], v[12:15], v[50:53]
	s_nop 2
	ds_read_b128 v[50:53], v104
	v_mfma_f32_16x16x32_bf16 v[0:3], v[78:81], v[12:15], v[0:3]
	s_waitcnt lgkmcnt(1)
	v_mfma_f32_16x16x32_bf16 v[54:57], v[74:77], v[12:15], v[54:57]
	ds_read_b128 v[74:77], v103
	ds_read_b128 v[78:81], v102
	s_waitcnt lgkmcnt(2)
	v_mfma_f32_16x16x32_bf16 v[50:53], v[50:53], v[12:15], v[58:61]
	s_nop 2
	ds_read_b128 v[58:61], v101
	ds_read_b128 v[82:85], v16
	s_waitcnt lgkmcnt(0)
	s_barrier
; __device__ __forceinline__ unsigned pk2(float lo, float hi) { return pg8::cvt_pk_bf16(lo, hi); }
; __device__ __forceinline__ f32x4 mma16(bf16x8 a, bf16x8 b, f32x4 c) { return __builtin_amdgcn_mfma_f32_16x16x32_bf16(a, b, c, 0, 0, 0); }
; __device__ __forceinline__ void ma_ret_item(const Params& p, ldsp lds, int item) {
;     ...
;         for (int ks = 0; ks < 2; ++ks) { const bf16x8 bf = ldfrag(VTt, (16 * wave + l15) * 72 + 32 * ks + 8 * q4);
; #pragma unroll
;             for (int i = 0; i < 16; ++i) acc[i] = mma16(ldfrag(KTt, (16 * i + l15) * 72 + 32 * ks + 8 * q4), bf, acc[i]); }
;         __syncthreads(); }
;     bf16_t* HL = (bf16_t*)(p.ws + WS_HL) + (((size_t)bh * 8 + sc) * 512 + es * 128 + 16 * wave + l15) * 256;
; #pragma unroll
;     for (int i = 0; i < 16; ++i) { u32x2 w; w.x = pk2(acc[i][0], acc[i][1]); w.y = pk2(acc[i][2], acc[i][3]); *(u32x2*)(HL + 16 * i + 4 * q4) = w; }
	v_mfma_f32_16x16x32_bf16 v[58:61], v[58:61], v[12:15], v[70:73]
	v_cvt_pk_bf16_f32 v0, v0, v1
	v_cvt_pk_bf16_f32 v1, v2, v3
	v_mfma_f32_16x16x32_bf16 v[62:65], v[74:77], v[12:15], v[62:65]
	s_nop 1
	v_or_b32_e32 v70, s0, v95
	v_mov_b32_e32 v71, s1
	v_lshl_add_u64 v[70:71], v[70:71], 0, s[8:9]
	v_readlane_b32 s0, v253, 34
	v_mfma_f32_16x16x32_bf16 v[66:69], v[78:81], v[12:15], v[66:69]
	v_readlane_b32 s1, v253, 35
	v_mov_b32_e32 v95, v17
	v_mfma_f32_16x16x32_bf16 v[4:7], v[82:85], v[12:15], v[4:7]
	v_lshlrev_b64 v[12:13], 9, v[70:71]
	v_lshl_add_u64 v[12:13], s[0:1], 0, v[12:13]
	v_lshl_add_u64 v[12:13], v[12:13], 0, v[94:95]
	global_store_dwordx2 v[12:13], v[0:1], off
	v_cvt_pk_bf16_f32 v0, v8, v9
	v_cvt_pk_bf16_f32 v1, v10, v11
	global_store_dwordx2 v[12:13], v[0:1], off offset:32
	v_cvt_pk_bf16_f32 v0, v18, v19
	v_cvt_pk_bf16_f32 v1, v20, v21
	global_store_dwordx2 v[12:13], v[0:1], off offset:64
	v_cvt_pk_bf16_f32 v0, v22, v23
	v_cvt_pk_bf16_f32 v1, v24, v25
	global_store_dwordx2 v[12:13], v[0:1], off offset:96
	v_cvt_pk_bf16_f32 v0, v26, v27
	v_cvt_pk_bf16_f32 v1, v28, v29
	global_store_dwordx2 v[12:13], v[0:1], off offset:128
	v_cvt_pk_bf16_f32 v0, v30, v31
	v_cvt_pk_bf16_f32 v1, v32, v33
	global_store_dwordx2 v[12:13], v[0:1], off offset:160
	v_cvt_pk_bf16_f32 v0, v38, v39
	v_cvt_pk_bf16_f32 v1, v40, v41
	global_store_dwordx2 v[12:13], v[0:1], off offset:192
	v_cvt_pk_bf16_f32 v0, v34, v35
	v_cvt_pk_bf16_f32 v1, v36, v37
	global_store_dwordx2 v[12:13], v[0:1], off offset:224
	v_cvt_pk_bf16_f32 v0, v46, v47
	v_cvt_pk_bf16_f32 v1, v48, v49
	global_store_dwordx2 v[12:13], v[0:1], off offset:256
	v_cvt_pk_bf16_f32 v0, v42, v43
	v_cvt_pk_bf16_f32 v1, v44, v45
	global_store_dwordx2 v[12:13], v[0:1], off offset:288
	v_cvt_pk_bf16_f32 v0, v54, v55
	v_cvt_pk_bf16_f32 v1, v56, v57
	global_store_dwordx2 v[12:13], v[0:1], off offset:320
	v_cvt_pk_bf16_f32 v0, v50, v51
	v_cvt_pk_bf16_f32 v1, v52, v53
	global_store_dwordx2 v[12:13], v[0:1], off offset:352
	v_cvt_pk_bf16_f32 v0, v62, v63
	v_cvt_pk_bf16_f32 v1, v64, v65
	global_store_dwordx2 v[12:13], v[0:1], off offset:384
	v_cvt_pk_bf16_f32 v0, v66, v67
	v_cvt_pk_bf16_f32 v1, v68, v69
	global_store_dwordx2 v[12:13], v[0:1], off offset:416
	v_cvt_pk_bf16_f32 v0, v58, v59
	v_cvt_pk_bf16_f32 v1, v60, v61
	global_store_dwordx2 v[12:13], v[0:1], off offset:448
	v_cvt_pk_bf16_f32 v0, v4, v5
	v_cvt_pk_bf16_f32 v1, v6, v7
	global_store_dwordx2 v[12:13], v[0:1], off offset:480
	s_cbranch_scc0 .LBB0_677
